# FFN-up epilogue: eight row-stat loads issued together with counted vmcnt (were load+vmcnt(0) x8)
# speedup vs baseline: 1.0184x; 1.0064x over previous
.LBB0_1335:
	s_lshl_b32 s8, s16, 8
	v_readlane_b32 s9, v255, 13
	v_and_b32_e32 v212, 15, v34
	v_bfe_u32 v220, v34, 4, 2
	s_add_i32 s8, s8, s9
	v_or_b32_e32 v170, s8, v212
	v_lshlrev_b32_e32 v210, 3, v220
	v_readlane_b32 s8, v255, 14
	s_lshl_b64 s[6:7], s[6:7], 2
	v_lshlrev_b32_e32 v146, 4, v220
	v_or_b32_e32 v211, s8, v210
	v_readlane_b32 s8, v255, 7
	v_lshl_or_b32 v192, s56, 8, v211
	s_add_u32 s6, s8, s6
	v_readlane_b32 s8, v255, 8
	s_addc_u32 s7, s8, s7
	v_ashrrev_i32_e32 v193, 31, v192
	v_lshl_add_u64 v[86:87], v[192:193], 2, s[6:7]
	v_readlane_b32 s6, v255, 5
	v_mov_b32_e32 v147, v0
	v_readlane_b32 s7, v255, 6
	v_ashrrev_i32_e32 v171, 31, v170
	v_lshlrev_b64 v[148:149], 6, v[170:171]
	v_lshl_add_u64 v[146:147], s[6:7], 0, v[146:147]
	v_lshl_add_u64 v[148:149], v[146:147], 0, v[148:149]
	global_load_dwordx4 v[38:41], v[86:87], off offset:16
	global_load_dwordx4 v[90:93], v[86:87], off
	global_load_dwordx4 v[34:37], v[86:87], off offset:528
	s_nop 0
	global_load_dwordx4 v[86:89], v[86:87], off offset:512
	v_or_b32_e32 v172, 16, v170
	global_load_dwordx4 v[162:165], v[148:149], off
	global_load_dwordx4 v[214:217], v[148:149], off offset:1024
	global_load_dwordx4 v[222:225], v[148:149], off offset:2048
	global_load_dwordx4 v[226:229], v[148:149], off offset:3072
	s_mov_b64 s[10:11], 0x2000
	v_lshl_add_u64 v[218:219], v[148:149], 0, s[10:11]
	global_load_dwordx4 v[242:245], v[218:219], off
	global_load_dwordx4 v[246:249], v[218:219], off offset:1024
	global_load_dwordx4 v[184:187], v[218:219], off offset:2048
	global_load_dwordx4 v[250:253], v[218:219], off offset:3072
	v_ashrrev_i32_e32 v173, 31, v172
	s_mov_b32 s6, 0x358637bd
	v_mov_b64_e32 v[200:201], s[6:7]
	s_mov_b32 s6, 0x3a800000
	v_or_b32_e32 v174, 32, v170
	v_ashrrev_i32_e32 v175, 31, v174
	v_or_b32_e32 v176, 48, v170
	v_ashrrev_i32_e32 v177, 31, v176
	s_cmp_lt_i32 s16, 32
	s_waitcnt vmcnt(7)
	v_mov_b32_e32 v148, v163
	v_mov_b32_e32 v149, v164
	v_mov_b32_e32 v163, v165
	v_pk_add_f32 v[148:149], v[148:149], v[162:163]
	v_lshlrev_b64 v[162:163], 6, v[172:173]
	v_lshl_add_u64 v[162:163], v[146:147], 0, v[162:163]
	v_pk_add_f32 v[148:149], v[148:149], v[148:149] op_sel:[0,1] op_sel_hi:[1,0]
	s_waitcnt vmcnt(6)
	v_mov_b32_e32 v162, v214
	v_mov_b32_e32 v163, v215
	v_mov_b32_e32 v164, v216
	v_mov_b32_e32 v165, v217
	v_mov_b32_e32 v168, v163
	v_mov_b32_e32 v169, v164
	v_mov_b32_e32 v163, v165
	v_mov_b32_e32 v149, v148
	v_pk_add_f32 v[162:163], v[168:169], v[162:163]
	s_nop 0
	v_permlane16_swap_b32_e32 v148, v149
	v_pk_add_f32 v[162:163], v[162:163], v[162:163] op_sel:[0,1] op_sel_hi:[1,0]
	v_add_f32_e32 v149, v148, v149
	v_mov_b32_e32 v148, v162
	s_nop 1
	v_permlane16_swap_b32_e32 v162, v148
	v_add_f32_e32 v148, v162, v148
	v_mov_b32_e32 v167, v149
	v_mov_b32_e32 v166, v148
	s_nop 0
	v_permlane32_swap_b32_e32 v149, v167
	v_permlane32_swap_b32_e32 v148, v166
	v_pk_add_f32 v[148:149], v[148:149], v[166:167]
	s_nop 0
	v_pk_fma_f32 v[190:191], v[148:149], s[6:7], v[200:201] op_sel_hi:[1,0,0]
	s_nop 0
	v_mul_f32_e32 v148, 0x4b800000, v191
	v_cmp_gt_f32_e32 vcc, s84, v191
	v_cmp_gt_f32_e64 s[12:13], s84, v190
	s_nop 0
	v_cndmask_b32_e32 v148, v191, v148, vcc
	v_rsq_f32_e32 v148, v148
	s_nop 0
	v_mul_f32_e32 v149, 0x45800000, v148
	v_cndmask_b32_e32 v198, v148, v149, vcc
	v_lshlrev_b64 v[148:149], 6, v[174:175]
	v_lshl_add_u64 v[148:149], v[146:147], 0, v[148:149]
	v_pk_fma_f32 v[96:97], v[96:97], v[198:199], v[92:93] op_sel_hi:[1,0,1]
	v_pk_fma_f32 v[94:95], v[94:95], v[198:199], v[90:91] op_sel_hi:[1,0,1]
	v_pk_fma_f32 v[84:85], v[84:85], v[198:199], v[88:89] op_sel_hi:[1,0,1]
	v_pk_fma_f32 v[82:83], v[82:83], v[198:199], v[86:87] op_sel_hi:[1,0,1]
	v_cvt_pk_bf16_f32 v94, v94, v95
	v_cvt_pk_bf16_f32 v95, v96, v97
	v_pk_fma_f32 v[144:145], v[144:145], v[198:199], v[40:41] op_sel_hi:[1,0,1]
	v_pk_fma_f32 v[96:97], v[142:143], v[198:199], v[38:39] op_sel_hi:[1,0,1]
	v_cvt_pk_bf16_f32 v82, v82, v83
	v_cvt_pk_bf16_f32 v83, v84, v85
	v_pk_fma_f32 v[140:141], v[140:141], v[198:199], v[36:37] op_sel_hi:[1,0,1]
	v_pk_fma_f32 v[84:85], v[138:139], v[198:199], v[34:35] op_sel_hi:[1,0,1]
	v_cvt_pk_bf16_f32 v96, v96, v97
	v_cvt_pk_bf16_f32 v97, v144, v145
	v_cvt_pk_bf16_f32 v84, v84, v85
	v_cvt_pk_bf16_f32 v85, v140, v141
	s_waitcnt vmcnt(5)
	v_mov_b32_e32 v162, v222
	v_mov_b32_e32 v163, v223
	v_mov_b32_e32 v164, v224
	v_mov_b32_e32 v165, v225
	v_mov_b32_e32 v148, v163
	v_mov_b32_e32 v149, v164
	v_mov_b32_e32 v163, v165
	v_pk_add_f32 v[148:149], v[148:149], v[162:163]
	s_nop 0
	v_pk_add_f32 v[148:149], v[148:149], v[148:149] op_sel:[0,1] op_sel_hi:[1,0]
	s_nop 0
	v_mov_b32_e32 v149, v148
	s_nop 1
	v_permlane16_swap_b32_e32 v148, v149
	v_add_f32_e32 v195, v148, v149
	v_lshlrev_b64 v[148:149], 6, v[176:177]
	v_lshl_add_u64 v[148:149], v[146:147], 0, v[148:149]
	v_mov_b32_e32 v197, v195
	s_nop 1
	v_permlane32_swap_b32_e32 v195, v197
	s_waitcnt vmcnt(4)
	v_mov_b32_e32 v162, v226
	v_mov_b32_e32 v163, v227
	v_mov_b32_e32 v164, v228
	v_mov_b32_e32 v165, v229
	v_mov_b32_e32 v148, v163
	v_mov_b32_e32 v149, v164
	v_mov_b32_e32 v163, v165
	v_pk_add_f32 v[148:149], v[148:149], v[162:163]
	v_add_u32_e32 v162, 0x80, v170
	v_pk_add_f32 v[148:149], v[148:149], v[148:149] op_sel:[0,1] op_sel_hi:[1,0]
	v_ashrrev_i32_e32 v163, 31, v162
	v_mov_b32_e32 v149, v148
	s_nop 1
	v_permlane16_swap_b32_e32 v148, v149
	v_add_f32_e32 v194, v148, v149
	v_lshlrev_b64 v[148:149], 6, v[162:163]
	v_lshl_add_u64 v[148:149], v[146:147], 0, v[148:149]
	v_mov_b32_e32 v196, v194
	s_nop 1
	v_permlane32_swap_b32_e32 v194, v196
	s_waitcnt vmcnt(3)
	v_mov_b32_e32 v164, v242
	v_mov_b32_e32 v165, v243
	v_mov_b32_e32 v166, v244
	v_mov_b32_e32 v167, v245
	v_mov_b32_e32 v148, v165
	v_mov_b32_e32 v149, v166
	v_mov_b32_e32 v165, v167
	v_pk_add_f32 v[148:149], v[148:149], v[164:165]
	v_add_u32_e32 v164, 0x90, v170
	v_pk_add_f32 v[148:149], v[148:149], v[148:149] op_sel:[0,1] op_sel_hi:[1,0]
	v_ashrrev_i32_e32 v165, 31, v164
	v_mov_b32_e32 v149, v148
	s_nop 1
	v_permlane16_swap_b32_e32 v148, v149
	v_add_f32_e32 v203, v148, v149
	v_lshlrev_b64 v[148:149], 6, v[164:165]
	v_lshl_add_u64 v[148:149], v[146:147], 0, v[148:149]
	v_mov_b32_e32 v205, v203
	s_nop 1
	v_permlane32_swap_b32_e32 v203, v205
	s_waitcnt vmcnt(2)
	v_mov_b32_e32 v166, v246
	v_mov_b32_e32 v167, v247
	v_mov_b32_e32 v168, v248
	v_mov_b32_e32 v169, v249
	v_mov_b32_e32 v148, v167
	v_mov_b32_e32 v149, v168
	v_mov_b32_e32 v167, v169
	v_pk_add_f32 v[148:149], v[148:149], v[166:167]
	v_add_u32_e32 v166, 0xa0, v170
	v_pk_add_f32 v[148:149], v[148:149], v[148:149] op_sel:[0,1] op_sel_hi:[1,0]
	v_ashrrev_i32_e32 v167, 31, v166
	v_mov_b32_e32 v149, v148
	s_nop 1
	v_permlane16_swap_b32_e32 v148, v149
	v_add_f32_e32 v202, v148, v149
	v_lshlrev_b64 v[148:149], 6, v[166:167]
	v_lshl_add_u64 v[148:149], v[146:147], 0, v[148:149]
	v_add_u32_e32 v168, 0xb0, v170
	v_ashrrev_i32_e32 v169, 31, v168
	v_mov_b32_e32 v204, v202
	s_nop 1
	v_permlane32_swap_b32_e32 v202, v204
	s_waitcnt vmcnt(1)
	v_mov_b32_e32 v148, v185
	v_mov_b32_e32 v149, v186
	v_mov_b32_e32 v185, v187
	v_pk_add_f32 v[148:149], v[148:149], v[184:185]
	s_nop 0
	v_pk_add_f32 v[148:149], v[148:149], v[148:149] op_sel:[0,1] op_sel_hi:[1,0]
	s_nop 0
	v_mov_b32_e32 v149, v148
	s_nop 1
	v_permlane16_swap_b32_e32 v148, v149
	v_add_f32_e32 v207, v148, v149
	v_lshlrev_b64 v[148:149], 6, v[168:169]
	v_lshl_add_u64 v[146:147], v[146:147], 0, v[148:149]
	v_mov_b32_e32 v209, v207
	s_nop 1
	v_permlane32_swap_b32_e32 v207, v209
	s_waitcnt vmcnt(0)
	v_mov_b32_e32 v146, v250
	v_mov_b32_e32 v147, v251
	v_mov_b32_e32 v148, v252
	v_mov_b32_e32 v149, v253
	v_mov_b32_e32 v184, v147
	v_mov_b32_e32 v185, v148
	v_mov_b32_e32 v147, v149
	v_pk_add_f32 v[146:147], v[184:185], v[146:147]
	s_nop 0
	v_pk_add_f32 v[146:147], v[146:147], v[146:147] op_sel:[0,1] op_sel_hi:[1,0]
	s_nop 0
	v_mov_b32_e32 v147, v146
	s_nop 1
	v_permlane16_swap_b32_e32 v146, v147
	v_add_f32_e32 v206, v146, v147
	v_mov_b32_e32 v208, v206
	s_nop 1
	v_permlane32_swap_b32_e32 v206, v208
	v_pk_add_f32 v[146:147], v[206:207], v[208:209]
	s_nop 0
	v_pk_fma_f32 v[146:147], v[146:147], s[6:7], v[200:201] op_sel_hi:[1,0,0]
	s_nop 0
	v_cmp_gt_f32_e32 vcc, s84, v146
	v_mul_f32_e32 v148, 0x4b800000, v146
	v_cmp_gt_f32_e64 s[14:15], s84, v147
	v_cndmask_b32_e32 v146, v146, v148, vcc
	v_rsq_f32_e32 v146, v146
	s_nop 0
	v_mul_f32_e32 v148, 0x45800000, v146
	v_cndmask_b32_e32 v146, v146, v148, vcc
	v_pk_fma_f32 v[60:61], v[60:61], v[146:147], v[92:93] op_sel_hi:[1,0,1]
	v_pk_fma_f32 v[58:59], v[58:59], v[146:147], v[90:91] op_sel_hi:[1,0,1]
	v_pk_fma_f32 v[64:65], v[64:65], v[146:147], v[88:89] op_sel_hi:[1,0,1]
	v_pk_fma_f32 v[62:63], v[62:63], v[146:147], v[86:87] op_sel_hi:[1,0,1]
	v_cvt_pk_bf16_f32 v58, v58, v59
	v_cvt_pk_bf16_f32 v59, v60, v61
	v_pk_fma_f32 v[136:137], v[136:137], v[146:147], v[40:41] op_sel_hi:[1,0,1]
	v_pk_fma_f32 v[60:61], v[134:135], v[146:147], v[38:39] op_sel_hi:[1,0,1]
	v_cvt_pk_bf16_f32 v62, v62, v63
	v_cvt_pk_bf16_f32 v63, v64, v65
	v_pk_fma_f32 v[132:133], v[132:133], v[146:147], v[36:37] op_sel_hi:[1,0,1]
	v_pk_fma_f32 v[64:65], v[130:131], v[146:147], v[34:35] op_sel_hi:[1,0,1]
	v_cvt_pk_bf16_f32 v60, v60, v61
	v_cvt_pk_bf16_f32 v61, v136, v137
	v_cvt_pk_bf16_f32 v64, v64, v65
	v_cvt_pk_bf16_f32 v65, v132, v133
	s_cbranch_scc1 .LBB0_1341
	s_sub_i32 s6, s16, 32
	s_mul_hi_u32 s7, s6, 0xb000
	s_mul_i32 s6, s6, 0xb000
	v_readlane_b32 s8, v255, 11
	s_add_u32 s6, s8, s6
	v_readlane_b32 s8, v255, 12
	s_addc_u32 s7, s8, s7
	v_cmp_gt_u32_e32 vcc, 2, v212
	v_lshl_add_u64 v[130:131], v[192:193], 1, s[6:7]
	s_and_b64 s[8:9], s[68:69], vcc
	s_and_saveexec_b64 s[6:7], s[8:9]
	s_cbranch_execz .LBB0_1338
	v_mul_u32_u24_e32 v132, 0x1600, v212
	v_lshlrev_b32_e32 v132, 1, v132
	v_mov_b32_e32 v133, v0
	v_lshl_add_u64 v[132:133], v[130:131], 0, v[132:133]
	global_store_dwordx4 v[132:133], v[94:97], off
	global_store_dwordx4 v[132:133], v[82:85], off offset:256
